# gdnpre forward substitution with all LDS operands fetched up front; both GEMM K-loop headers aligned to 256 bytes
# baseline (speedup 1.0000x reference)
.LBB0_60:
	s_or_b64 exec, exec, s[10:11]
	v_mov_b32_e32 v2, s8
	s_waitcnt lgkmcnt(0)
	s_barrier
	ds_read_b32 v2, v2
	s_waitcnt lgkmcnt(0)
	v_readfirstlane_b32 s2, v2
	s_ashr_i32 s10, s2, 3
	s_and_b32 s10, s10, -8
	s_or_b32 s12, s10, s48
	s_cmp_gt_i32 s12, 39
	s_mov_b64 s[10:11], -1
	s_cbranch_scc1 .LBB0_55
	s_lshl_b32 s11, s2, 7
	s_lshl_b32 s10, s12, 10
	s_and_b32 s11, s11, 0x380
	s_or_b32 s13, s10, s11
	s_bfe_u32 s12, s2, 0x30003
	s_lshl_b32 s49, s12, 7
	s_mul_i32 s10, s13, 0x1820
	s_mul_hi_i32 s2, s13, 0x1820
	s_add_u32 s10, s34, s10
	s_addc_u32 s11, s35, s2
	s_lshl_b32 s2, s12, 18
	v_readlane_b32 s42, v246, 23
	s_add_u32 s42, s42, s2
	v_readlane_b32 s43, v246, 24
	v_readfirstlane_b32 s56, v1
	v_add_u32_e32 v6, 0x4000, v1
	s_waitcnt lgkmcnt(0)
	s_barrier
	s_addc_u32 s43, s43, 0
	v_lshl_add_u64 v[2:3], v[66:67], 1, s[10:11]
	s_mov_b32 m0, s56
	v_readfirstlane_b32 s57, v6
	v_add_u32_e32 v8, 0x1000, v1
	global_load_lds_dwordx4 v[2:3], off
	v_lshl_add_u64 v[4:5], v[68:69], 1, s[42:43]
	s_mov_b32 m0, s57
	v_readfirstlane_b32 s58, v8
	v_add_u32_e32 v10, 0x5000, v1
	global_load_lds_dwordx4 v[4:5], off
	v_lshl_add_u64 v[6:7], v[70:71], 1, s[10:11]
	s_mov_b32 m0, s58
	v_readfirstlane_b32 s59, v10
	v_add_u32_e32 v12, 0x2000, v1
	global_load_lds_dwordx4 v[6:7], off
	v_lshl_add_u64 v[8:9], v[72:73], 1, s[42:43]
	s_mov_b32 m0, s59
	v_readfirstlane_b32 s60, v12
	v_add_u32_e32 v14, 0x6000, v1
	global_load_lds_dwordx4 v[8:9], off
	v_lshl_add_u64 v[10:11], v[74:75], 1, s[10:11]
	s_mov_b32 m0, s60
	v_readfirstlane_b32 s61, v14
	v_add_u32_e32 v16, 0x3000, v1
	global_load_lds_dwordx4 v[10:11], off
	v_lshl_add_u64 v[12:13], v[76:77], 1, s[42:43]
	s_mov_b32 m0, s61
	v_readfirstlane_b32 s97, v16
	v_add_u32_e32 v18, 0x7000, v1
	global_load_lds_dwordx4 v[12:13], off
	v_lshl_add_u64 v[14:15], v[78:79], 1, s[10:11]
	s_mov_b32 m0, s97
	v_readfirstlane_b32 s44, v18
	global_load_lds_dwordx4 v[14:15], off
	v_lshl_add_u64 v[16:17], v[80:81], 1, s[42:43]
	s_mov_b32 m0, s44
	v_add_u32_e32 v20, 0x8000, v1
	global_load_lds_dwordx4 v[16:17], off
	s_waitcnt vmcnt(0)
	v_readfirstlane_b32 s42, v20
	v_add_u32_e32 v20, 0xc000, v1
	s_waitcnt lgkmcnt(0)
	s_barrier
	v_lshl_add_u64 v[18:19], v[2:3], 0, s[98:99]
	s_mov_b32 m0, s42
	v_readfirstlane_b32 s43, v20
	v_add_u32_e32 v20, 0x9000, v1
	global_load_lds_dwordx4 v[18:19], off
	v_lshl_add_u64 v[18:19], v[4:5], 0, s[98:99]
	s_mov_b32 m0, s43
	v_readfirstlane_b32 s50, v20
	v_add_u32_e32 v20, 0xd000, v1
	global_load_lds_dwordx4 v[18:19], off
	v_lshl_add_u64 v[18:19], v[6:7], 0, s[98:99]
	s_mov_b32 m0, s50
	v_readfirstlane_b32 s51, v20
	v_add_u32_e32 v20, 0xa000, v1
	global_load_lds_dwordx4 v[18:19], off
	v_lshl_add_u64 v[18:19], v[8:9], 0, s[98:99]
	s_mov_b32 m0, s51
	v_readfirstlane_b32 s52, v20
	v_add_u32_e32 v20, 0xe000, v1
	global_load_lds_dwordx4 v[18:19], off
	v_lshl_add_u64 v[18:19], v[10:11], 0, s[98:99]
	s_mov_b32 m0, s52
	v_readfirstlane_b32 s53, v20
	v_add_u32_e32 v20, 0xb000, v1
	global_load_lds_dwordx4 v[18:19], off
	v_lshl_add_u64 v[18:19], v[12:13], 0, s[98:99]
	s_mov_b32 m0, s53
	v_readfirstlane_b32 s54, v20
	v_add_u32_e32 v20, 0xf000, v1
	global_load_lds_dwordx4 v[18:19], off
	v_lshl_add_u64 v[18:19], v[14:15], 0, s[98:99]
	s_mov_b32 m0, s54
	v_readfirstlane_b32 s55, v20
	global_load_lds_dwordx4 v[18:19], off
	v_lshl_add_u64 v[18:19], v[16:17], 0, s[98:99]
	s_mov_b32 m0, s55
	s_mov_b64 vcc, 0x100
	global_load_lds_dwordx4 v[18:19], off
	v_add_u32_e32 v19, v102, v104
	ds_read_b128 v[20:23], v19 offset:16384
	ds_read_b128 v[32:35], v19 offset:18432
	ds_read_b128 v[40:43], v19 offset:20480
	ds_read_b128 v[126:129], v19 offset:19456
	ds_read_b128 v[48:51], v19 offset:22528
	ds_read_b128 v[130:133], v19 offset:21504
	v_add_u32_e32 v18, v102, v103
	ds_read_b128 v[24:27], v18
	ds_read_b128 v[52:55], v18 offset:2048
	ds_read_b128 v[98:101], v18 offset:4096
	ds_read_b128 v[118:121], v18 offset:6144
	ds_read_b128 v[122:125], v19 offset:17408
	ds_read_b128 v[134:137], v19 offset:23552
	s_waitcnt lgkmcnt(0)
	v_mfma_f32_16x16x32_bf16 v[28:31], v[20:23], v[24:27], 0
	v_lshl_add_u64 v[64:65], v[2:3], 0, vcc
	s_mov_b32 m0, s56
	s_mov_b64 s[62:63], 0x180
	v_mfma_f32_16x16x32_bf16 v[36:39], v[32:35], v[24:27], 0
	v_mfma_f32_16x16x32_bf16 v[44:47], v[40:43], v[24:27], 0
	v_mfma_f32_16x16x32_bf16 v[24:27], v[48:51], v[24:27], 0
	v_mfma_f32_16x16x32_bf16 v[56:59], v[20:23], v[52:55], 0
	v_mfma_f32_16x16x32_bf16 v[60:63], v[32:35], v[52:55], 0
	v_mfma_f32_16x16x32_bf16 v[94:97], v[40:43], v[52:55], 0
	v_mfma_f32_16x16x32_bf16 v[52:55], v[48:51], v[52:55], 0
	v_mfma_f32_16x16x32_bf16 v[106:109], v[20:23], v[98:101], 0
	v_mfma_f32_16x16x32_bf16 v[110:113], v[32:35], v[98:101], 0
	v_mfma_f32_16x16x32_bf16 v[114:117], v[40:43], v[98:101], 0
	v_mfma_f32_16x16x32_bf16 v[98:101], v[48:51], v[98:101], 0
	v_mfma_f32_16x16x32_bf16 v[20:23], v[20:23], v[118:121], 0
	v_mfma_f32_16x16x32_bf16 v[32:35], v[32:35], v[118:121], 0
	v_mfma_f32_16x16x32_bf16 v[40:43], v[40:43], v[118:121], 0
	v_mfma_f32_16x16x32_bf16 v[48:51], v[48:51], v[118:121], 0
	ds_read_b128 v[118:121], v18 offset:1024
	s_waitcnt lgkmcnt(0)
	v_mfma_f32_16x16x32_bf16 v[28:31], v[122:125], v[118:121], v[28:31]
	v_mfma_f32_16x16x32_bf16 v[36:39], v[126:129], v[118:121], v[36:39]
	v_mfma_f32_16x16x32_bf16 v[44:47], v[130:133], v[118:121], v[44:47]
	v_mfma_f32_16x16x32_bf16 v[24:27], v[134:137], v[118:121], v[24:27]
	ds_read_b128 v[118:121], v18 offset:3072
	s_waitcnt lgkmcnt(0)
	v_mfma_f32_16x16x32_bf16 v[56:59], v[122:125], v[118:121], v[56:59]
	v_mfma_f32_16x16x32_bf16 v[60:63], v[126:129], v[118:121], v[60:63]
	v_mfma_f32_16x16x32_bf16 v[94:97], v[130:133], v[118:121], v[94:97]
	v_mfma_f32_16x16x32_bf16 v[52:55], v[134:137], v[118:121], v[52:55]
	ds_read_b128 v[118:121], v18 offset:5120
	s_waitcnt lgkmcnt(0)
	v_mfma_f32_16x16x32_bf16 v[106:109], v[122:125], v[118:121], v[106:109]
	v_mfma_f32_16x16x32_bf16 v[110:113], v[126:129], v[118:121], v[110:113]
	v_mfma_f32_16x16x32_bf16 v[114:117], v[130:133], v[118:121], v[114:117]
	v_mfma_f32_16x16x32_bf16 v[98:101], v[134:137], v[118:121], v[98:101]
	ds_read_b128 v[118:121], v18 offset:7168
	s_waitcnt vmcnt(0)
	s_waitcnt lgkmcnt(0)
	s_barrier
	global_load_lds_dwordx4 v[64:65], off
	v_lshl_add_u64 v[64:65], v[4:5], 0, vcc
	s_mov_b32 m0, s57
	s_waitcnt lgkmcnt(0)
	v_mfma_f32_16x16x32_bf16 v[20:23], v[122:125], v[118:121], v[20:23]
	global_load_lds_dwordx4 v[64:65], off
	v_lshl_add_u64 v[64:65], v[6:7], 0, vcc
	s_mov_b32 m0, s58
	v_mfma_f32_16x16x32_bf16 v[32:35], v[126:129], v[118:121], v[32:35]
	global_load_lds_dwordx4 v[64:65], off
	v_lshl_add_u64 v[64:65], v[8:9], 0, vcc
	s_mov_b32 m0, s59
	v_mfma_f32_16x16x32_bf16 v[40:43], v[130:133], v[118:121], v[40:43]
	global_load_lds_dwordx4 v[64:65], off
	v_lshl_add_u64 v[64:65], v[10:11], 0, vcc
	s_mov_b32 m0, s60
	v_mfma_f32_16x16x32_bf16 v[48:51], v[134:137], v[118:121], v[48:51]
	global_load_lds_dwordx4 v[64:65], off
	v_lshl_add_u64 v[64:65], v[12:13], 0, vcc
	s_mov_b32 m0, s61
	s_nop 0
	global_load_lds_dwordx4 v[64:65], off
	v_lshl_add_u64 v[64:65], v[14:15], 0, vcc
	s_mov_b32 m0, s97
	s_nop 0
	global_load_lds_dwordx4 v[64:65], off
	v_lshl_add_u64 v[64:65], v[16:17], 0, vcc
	s_mov_b32 m0, s44
	s_nop 0
	global_load_lds_dwordx4 v[64:65], off
	ds_read_b128 v[122:125], v19 offset:49152
	ds_read_b128 v[118:121], v18 offset:32768
	ds_read_b128 v[126:129], v19 offset:51200
	ds_read_b128 v[130:133], v19 offset:53248
	ds_read_b128 v[134:137], v19 offset:55296
	s_waitcnt lgkmcnt(0)
	v_mfma_f32_16x16x32_bf16 v[28:31], v[122:125], v[118:121], v[28:31]
	v_lshl_add_u64 v[64:65], v[2:3], 0, s[62:63]
	s_mov_b32 m0, s42
	v_mfma_f32_16x16x32_bf16 v[36:39], v[126:129], v[118:121], v[36:39]
	v_mfma_f32_16x16x32_bf16 v[44:47], v[130:133], v[118:121], v[44:47]
	v_mfma_f32_16x16x32_bf16 v[24:27], v[134:137], v[118:121], v[24:27]
	ds_read_b128 v[118:121], v18 offset:34816
	s_waitcnt lgkmcnt(0)
	v_mfma_f32_16x16x32_bf16 v[56:59], v[122:125], v[118:121], v[56:59]
	v_mfma_f32_16x16x32_bf16 v[60:63], v[126:129], v[118:121], v[60:63]
	v_mfma_f32_16x16x32_bf16 v[94:97], v[130:133], v[118:121], v[94:97]
	v_mfma_f32_16x16x32_bf16 v[52:55], v[134:137], v[118:121], v[52:55]
	ds_read_b128 v[118:121], v18 offset:36864
	s_waitcnt lgkmcnt(0)
	v_mfma_f32_16x16x32_bf16 v[106:109], v[122:125], v[118:121], v[106:109]
	v_mfma_f32_16x16x32_bf16 v[110:113], v[126:129], v[118:121], v[110:113]
	v_mfma_f32_16x16x32_bf16 v[114:117], v[130:133], v[118:121], v[114:117]
	v_mfma_f32_16x16x32_bf16 v[98:101], v[134:137], v[118:121], v[98:101]
	ds_read_b128 v[118:121], v18 offset:38912
	s_waitcnt lgkmcnt(0)
	v_mfma_f32_16x16x32_bf16 v[20:23], v[122:125], v[118:121], v[20:23]
	ds_read_b128 v[122:125], v19 offset:50176
	v_mfma_f32_16x16x32_bf16 v[32:35], v[126:129], v[118:121], v[32:35]
	ds_read_b128 v[126:129], v19 offset:52224
	v_mfma_f32_16x16x32_bf16 v[40:43], v[130:133], v[118:121], v[40:43]
	ds_read_b128 v[130:133], v19 offset:54272
	v_mfma_f32_16x16x32_bf16 v[48:51], v[134:137], v[118:121], v[48:51]
	ds_read_b128 v[134:137], v19 offset:56320
	ds_read_b128 v[118:121], v18 offset:33792
	s_waitcnt lgkmcnt(0)
	v_mfma_f32_16x16x32_bf16 v[28:31], v[122:125], v[118:121], v[28:31]
	v_mfma_f32_16x16x32_bf16 v[36:39], v[126:129], v[118:121], v[36:39]
	v_mfma_f32_16x16x32_bf16 v[44:47], v[130:133], v[118:121], v[44:47]
	v_mfma_f32_16x16x32_bf16 v[24:27], v[134:137], v[118:121], v[24:27]
	ds_read_b128 v[118:121], v18 offset:35840
	s_waitcnt lgkmcnt(0)
	v_mfma_f32_16x16x32_bf16 v[56:59], v[122:125], v[118:121], v[56:59]
	v_mfma_f32_16x16x32_bf16 v[60:63], v[126:129], v[118:121], v[60:63]
	v_mfma_f32_16x16x32_bf16 v[94:97], v[130:133], v[118:121], v[94:97]
	v_mfma_f32_16x16x32_bf16 v[52:55], v[134:137], v[118:121], v[52:55]
	ds_read_b128 v[118:121], v18 offset:37888
	s_waitcnt lgkmcnt(0)
	v_mfma_f32_16x16x32_bf16 v[106:109], v[122:125], v[118:121], v[106:109]
	v_mfma_f32_16x16x32_bf16 v[110:113], v[126:129], v[118:121], v[110:113]
	v_mfma_f32_16x16x32_bf16 v[114:117], v[130:133], v[118:121], v[114:117]
	v_mfma_f32_16x16x32_bf16 v[98:101], v[134:137], v[118:121], v[98:101]
	ds_read_b128 v[118:121], v18 offset:39936
	s_waitcnt vmcnt(0)
	s_waitcnt lgkmcnt(0)
	s_barrier
	global_load_lds_dwordx4 v[64:65], off
	v_lshl_add_u64 v[64:65], v[4:5], 0, s[62:63]
	s_mov_b32 m0, s43
	s_waitcnt lgkmcnt(0)
	v_mfma_f32_16x16x32_bf16 v[20:23], v[122:125], v[118:121], v[20:23]
	global_load_lds_dwordx4 v[64:65], off
	v_lshl_add_u64 v[64:65], v[6:7], 0, s[62:63]
	s_mov_b32 m0, s50
	v_mfma_f32_16x16x32_bf16 v[32:35], v[126:129], v[118:121], v[32:35]
	global_load_lds_dwordx4 v[64:65], off
	v_lshl_add_u64 v[64:65], v[8:9], 0, s[62:63]
	s_mov_b32 m0, s51
	v_mfma_f32_16x16x32_bf16 v[40:43], v[130:133], v[118:121], v[40:43]
	global_load_lds_dwordx4 v[64:65], off
	v_lshl_add_u64 v[64:65], v[10:11], 0, s[62:63]
	s_mov_b32 m0, s52
	v_mfma_f32_16x16x32_bf16 v[48:51], v[134:137], v[118:121], v[48:51]
	global_load_lds_dwordx4 v[64:65], off
	v_lshl_add_u64 v[64:65], v[12:13], 0, s[62:63]
	s_mov_b32 m0, s53
	s_nop 0
	global_load_lds_dwordx4 v[64:65], off
	v_lshl_add_u64 v[64:65], v[14:15], 0, s[62:63]
	s_mov_b32 m0, s54
	s_nop 0
	global_load_lds_dwordx4 v[64:65], off
	v_lshl_add_u64 v[64:65], v[16:17], 0, s[62:63]
	s_mov_b32 m0, s55
	s_nop 0
	global_load_lds_dwordx4 v[64:65], off
	ds_read_b128 v[122:125], v19 offset:16384
	ds_read_b128 v[118:121], v18
	ds_read_b128 v[126:129], v19 offset:18432
	ds_read_b128 v[130:133], v19 offset:20480
	ds_read_b128 v[134:137], v19 offset:22528
	s_waitcnt lgkmcnt(0)
	v_mfma_f32_16x16x32_bf16 v[28:31], v[122:125], v[118:121], v[28:31]
	v_lshl_add_u64 v[64:65], v[2:3], 0, s[94:95]
	s_mov_b32 m0, s56
	v_mfma_f32_16x16x32_bf16 v[36:39], v[126:129], v[118:121], v[36:39]
	v_mfma_f32_16x16x32_bf16 v[44:47], v[130:133], v[118:121], v[44:47]
	v_mfma_f32_16x16x32_bf16 v[24:27], v[134:137], v[118:121], v[24:27]
	ds_read_b128 v[118:121], v18 offset:2048
	s_waitcnt lgkmcnt(0)
	v_mfma_f32_16x16x32_bf16 v[56:59], v[122:125], v[118:121], v[56:59]
	v_mfma_f32_16x16x32_bf16 v[60:63], v[126:129], v[118:121], v[60:63]
	v_mfma_f32_16x16x32_bf16 v[94:97], v[130:133], v[118:121], v[94:97]
	v_mfma_f32_16x16x32_bf16 v[52:55], v[134:137], v[118:121], v[52:55]
	ds_read_b128 v[118:121], v18 offset:4096
	s_waitcnt lgkmcnt(0)
	v_mfma_f32_16x16x32_bf16 v[106:109], v[122:125], v[118:121], v[106:109]
	v_mfma_f32_16x16x32_bf16 v[110:113], v[126:129], v[118:121], v[110:113]
	v_mfma_f32_16x16x32_bf16 v[114:117], v[130:133], v[118:121], v[114:117]
	v_mfma_f32_16x16x32_bf16 v[98:101], v[134:137], v[118:121], v[98:101]
	ds_read_b128 v[118:121], v18 offset:6144
	s_waitcnt lgkmcnt(0)
	v_mfma_f32_16x16x32_bf16 v[20:23], v[122:125], v[118:121], v[20:23]
	ds_read_b128 v[122:125], v19 offset:17408
	v_mfma_f32_16x16x32_bf16 v[32:35], v[126:129], v[118:121], v[32:35]
	ds_read_b128 v[126:129], v19 offset:19456
	v_mfma_f32_16x16x32_bf16 v[40:43], v[130:133], v[118:121], v[40:43]
	ds_read_b128 v[130:133], v19 offset:21504
	v_mfma_f32_16x16x32_bf16 v[48:51], v[134:137], v[118:121], v[48:51]
	ds_read_b128 v[134:137], v19 offset:23552
	ds_read_b128 v[118:121], v18 offset:1024
	s_waitcnt lgkmcnt(0)
	v_mfma_f32_16x16x32_bf16 v[28:31], v[122:125], v[118:121], v[28:31]
	v_mfma_f32_16x16x32_bf16 v[36:39], v[126:129], v[118:121], v[36:39]
	v_mfma_f32_16x16x32_bf16 v[44:47], v[130:133], v[118:121], v[44:47]
	v_mfma_f32_16x16x32_bf16 v[24:27], v[134:137], v[118:121], v[24:27]
	ds_read_b128 v[118:121], v18 offset:3072
	s_waitcnt lgkmcnt(0)
	v_mfma_f32_16x16x32_bf16 v[56:59], v[122:125], v[118:121], v[56:59]
	v_mfma_f32_16x16x32_bf16 v[60:63], v[126:129], v[118:121], v[60:63]
	v_mfma_f32_16x16x32_bf16 v[94:97], v[130:133], v[118:121], v[94:97]
	v_mfma_f32_16x16x32_bf16 v[52:55], v[134:137], v[118:121], v[52:55]
	ds_read_b128 v[118:121], v18 offset:5120
	s_waitcnt lgkmcnt(0)
	v_mfma_f32_16x16x32_bf16 v[106:109], v[122:125], v[118:121], v[106:109]
	v_mfma_f32_16x16x32_bf16 v[110:113], v[126:129], v[118:121], v[110:113]
	v_mfma_f32_16x16x32_bf16 v[114:117], v[130:133], v[118:121], v[114:117]
	v_mfma_f32_16x16x32_bf16 v[98:101], v[134:137], v[118:121], v[98:101]
	ds_read_b128 v[118:121], v18 offset:7168
	s_waitcnt vmcnt(0)
	s_waitcnt lgkmcnt(0)
	s_barrier
	global_load_lds_dwordx4 v[64:65], off
	v_lshl_add_u64 v[64:65], v[4:5], 0, s[94:95]
	s_mov_b32 m0, s57
	s_waitcnt lgkmcnt(0)
	v_mfma_f32_16x16x32_bf16 v[20:23], v[122:125], v[118:121], v[20:23]
	global_load_lds_dwordx4 v[64:65], off
	v_lshl_add_u64 v[64:65], v[6:7], 0, s[94:95]
	s_mov_b32 m0, s58
	v_mfma_f32_16x16x32_bf16 v[32:35], v[126:129], v[118:121], v[32:35]
	global_load_lds_dwordx4 v[64:65], off
	v_lshl_add_u64 v[64:65], v[8:9], 0, s[94:95]
	s_mov_b32 m0, s59
	v_mfma_f32_16x16x32_bf16 v[40:43], v[130:133], v[118:121], v[40:43]
	global_load_lds_dwordx4 v[64:65], off
	v_lshl_add_u64 v[64:65], v[10:11], 0, s[94:95]
	s_mov_b32 m0, s60
	v_mfma_f32_16x16x32_bf16 v[48:51], v[134:137], v[118:121], v[48:51]
	global_load_lds_dwordx4 v[64:65], off
	v_lshl_add_u64 v[64:65], v[12:13], 0, s[94:95]
	s_mov_b32 m0, s61
	s_nop 0
	global_load_lds_dwordx4 v[64:65], off
	v_lshl_add_u64 v[64:65], v[14:15], 0, s[94:95]
	s_mov_b32 m0, s97
	s_nop 0
	global_load_lds_dwordx4 v[64:65], off
	v_lshl_add_u64 v[64:65], v[16:17], 0, s[94:95]
	s_mov_b32 m0, s44
	s_nop 0
	global_load_lds_dwordx4 v[64:65], off
	ds_read_b128 v[122:125], v19 offset:49152
	ds_read_b128 v[118:121], v18 offset:32768
	ds_read_b128 v[126:129], v19 offset:51200
	ds_read_b128 v[130:133], v19 offset:53248
	ds_read_b128 v[134:137], v19 offset:55296
	s_waitcnt lgkmcnt(0)
	v_mfma_f32_16x16x32_bf16 v[28:31], v[122:125], v[118:121], v[28:31]
	v_lshl_add_u64 v[64:65], v[2:3], 0, s[36:37]
	s_mov_b32 m0, s42
	v_mfma_f32_16x16x32_bf16 v[36:39], v[126:129], v[118:121], v[36:39]
	v_mfma_f32_16x16x32_bf16 v[44:47], v[130:133], v[118:121], v[44:47]
	v_mfma_f32_16x16x32_bf16 v[24:27], v[134:137], v[118:121], v[24:27]
	ds_read_b128 v[118:121], v18 offset:34816
	s_waitcnt lgkmcnt(0)
	v_mfma_f32_16x16x32_bf16 v[56:59], v[122:125], v[118:121], v[56:59]
	v_mfma_f32_16x16x32_bf16 v[60:63], v[126:129], v[118:121], v[60:63]
	v_mfma_f32_16x16x32_bf16 v[94:97], v[130:133], v[118:121], v[94:97]
	v_mfma_f32_16x16x32_bf16 v[52:55], v[134:137], v[118:121], v[52:55]
	ds_read_b128 v[118:121], v18 offset:36864
	s_waitcnt lgkmcnt(0)
	v_mfma_f32_16x16x32_bf16 v[106:109], v[122:125], v[118:121], v[106:109]
	v_mfma_f32_16x16x32_bf16 v[110:113], v[126:129], v[118:121], v[110:113]
	v_mfma_f32_16x16x32_bf16 v[114:117], v[130:133], v[118:121], v[114:117]
	v_mfma_f32_16x16x32_bf16 v[98:101], v[134:137], v[118:121], v[98:101]
	ds_read_b128 v[118:121], v18 offset:38912
	s_waitcnt lgkmcnt(0)
	v_mfma_f32_16x16x32_bf16 v[20:23], v[122:125], v[118:121], v[20:23]
	ds_read_b128 v[122:125], v19 offset:50176
	v_mfma_f32_16x16x32_bf16 v[32:35], v[126:129], v[118:121], v[32:35]
	ds_read_b128 v[126:129], v19 offset:52224
	v_mfma_f32_16x16x32_bf16 v[40:43], v[130:133], v[118:121], v[40:43]
	ds_read_b128 v[130:133], v19 offset:54272
	v_mfma_f32_16x16x32_bf16 v[48:51], v[134:137], v[118:121], v[48:51]
	ds_read_b128 v[134:137], v19 offset:56320
	ds_read_b128 v[118:121], v18 offset:33792
	s_waitcnt lgkmcnt(0)
	v_mfma_f32_16x16x32_bf16 v[28:31], v[122:125], v[118:121], v[28:31]
	v_mfma_f32_16x16x32_bf16 v[36:39], v[126:129], v[118:121], v[36:39]
	v_mfma_f32_16x16x32_bf16 v[44:47], v[130:133], v[118:121], v[44:47]
	v_mfma_f32_16x16x32_bf16 v[24:27], v[134:137], v[118:121], v[24:27]
	ds_read_b128 v[118:121], v18 offset:35840
	s_waitcnt lgkmcnt(0)
	v_mfma_f32_16x16x32_bf16 v[56:59], v[122:125], v[118:121], v[56:59]
	v_mfma_f32_16x16x32_bf16 v[60:63], v[126:129], v[118:121], v[60:63]
	v_mfma_f32_16x16x32_bf16 v[94:97], v[130:133], v[118:121], v[94:97]
	v_mfma_f32_16x16x32_bf16 v[52:55], v[134:137], v[118:121], v[52:55]
	ds_read_b128 v[118:121], v18 offset:37888
	s_waitcnt lgkmcnt(0)
	v_mfma_f32_16x16x32_bf16 v[106:109], v[122:125], v[118:121], v[106:109]
	v_mfma_f32_16x16x32_bf16 v[110:113], v[126:129], v[118:121], v[110:113]
	v_mfma_f32_16x16x32_bf16 v[114:117], v[130:133], v[118:121], v[114:117]
	v_mfma_f32_16x16x32_bf16 v[98:101], v[134:137], v[118:121], v[98:101]
	ds_read_b128 v[118:121], v18 offset:39936
	s_waitcnt vmcnt(0)
	s_waitcnt lgkmcnt(0)
	s_barrier
	global_load_lds_dwordx4 v[64:65], off
	v_lshl_add_u64 v[64:65], v[4:5], 0, s[36:37]
	s_mov_b32 m0, s43
	s_waitcnt lgkmcnt(0)
	v_mfma_f32_16x16x32_bf16 v[20:23], v[122:125], v[118:121], v[20:23]
	global_load_lds_dwordx4 v[64:65], off
	v_lshl_add_u64 v[64:65], v[6:7], 0, s[36:37]
	s_mov_b32 m0, s50
	v_mfma_f32_16x16x32_bf16 v[32:35], v[126:129], v[118:121], v[32:35]
	global_load_lds_dwordx4 v[64:65], off
	v_lshl_add_u64 v[64:65], v[8:9], 0, s[36:37]
	s_mov_b32 m0, s51
	v_mfma_f32_16x16x32_bf16 v[40:43], v[130:133], v[118:121], v[40:43]
	global_load_lds_dwordx4 v[64:65], off
	v_lshl_add_u64 v[64:65], v[10:11], 0, s[36:37]
	s_mov_b32 m0, s52
	v_mfma_f32_16x16x32_bf16 v[48:51], v[134:137], v[118:121], v[48:51]
	global_load_lds_dwordx4 v[64:65], off
	v_lshl_add_u64 v[64:65], v[12:13], 0, s[36:37]
	s_mov_b32 m0, s53
	s_nop 0
	global_load_lds_dwordx4 v[64:65], off
	v_lshl_add_u64 v[64:65], v[14:15], 0, s[36:37]
	s_mov_b32 m0, s54
	s_nop 0
	global_load_lds_dwordx4 v[64:65], off
	v_lshl_add_u64 v[64:65], v[16:17], 0, s[36:37]
	s_mov_b32 m0, s55
	s_nop 0
	global_load_lds_dwordx4 v[64:65], off
	ds_read_b128 v[122:125], v19 offset:16384
	ds_read_b128 v[118:121], v18
	ds_read_b128 v[126:129], v19 offset:18432
	ds_read_b128 v[130:133], v19 offset:20480
	ds_read_b128 v[134:137], v19 offset:22528
	s_waitcnt lgkmcnt(0)
	v_mfma_f32_16x16x32_bf16 v[28:31], v[122:125], v[118:121], v[28:31]
	v_lshl_add_u64 v[64:65], v[2:3], 0, s[22:23]
	s_mov_b32 m0, s56
	v_lshl_add_u64 v[2:3], v[2:3], 0, s[26:27]
	v_mfma_f32_16x16x32_bf16 v[36:39], v[126:129], v[118:121], v[36:39]
	v_mfma_f32_16x16x32_bf16 v[44:47], v[130:133], v[118:121], v[44:47]
	v_mfma_f32_16x16x32_bf16 v[24:27], v[134:137], v[118:121], v[24:27]
	ds_read_b128 v[118:121], v18 offset:2048
	s_waitcnt lgkmcnt(0)
	v_mfma_f32_16x16x32_bf16 v[56:59], v[122:125], v[118:121], v[56:59]
	v_mfma_f32_16x16x32_bf16 v[60:63], v[126:129], v[118:121], v[60:63]
	v_mfma_f32_16x16x32_bf16 v[94:97], v[130:133], v[118:121], v[94:97]
	v_mfma_f32_16x16x32_bf16 v[52:55], v[134:137], v[118:121], v[52:55]
	ds_read_b128 v[118:121], v18 offset:4096
	s_waitcnt lgkmcnt(0)
	v_mfma_f32_16x16x32_bf16 v[106:109], v[122:125], v[118:121], v[106:109]
	v_mfma_f32_16x16x32_bf16 v[110:113], v[126:129], v[118:121], v[110:113]
	v_mfma_f32_16x16x32_bf16 v[114:117], v[130:133], v[118:121], v[114:117]
	v_mfma_f32_16x16x32_bf16 v[98:101], v[134:137], v[118:121], v[98:101]
	ds_read_b128 v[118:121], v18 offset:6144
	s_waitcnt lgkmcnt(0)
	v_mfma_f32_16x16x32_bf16 v[20:23], v[122:125], v[118:121], v[20:23]
	ds_read_b128 v[122:125], v19 offset:17408
	v_mfma_f32_16x16x32_bf16 v[32:35], v[126:129], v[118:121], v[32:35]
	ds_read_b128 v[126:129], v19 offset:19456
	v_mfma_f32_16x16x32_bf16 v[40:43], v[130:133], v[118:121], v[40:43]
	ds_read_b128 v[130:133], v19 offset:21504
	v_mfma_f32_16x16x32_bf16 v[48:51], v[134:137], v[118:121], v[48:51]
	ds_read_b128 v[134:137], v19 offset:23552
	ds_read_b128 v[118:121], v18 offset:1024
	s_waitcnt lgkmcnt(0)
	v_mfma_f32_16x16x32_bf16 v[28:31], v[122:125], v[118:121], v[28:31]
	v_mfma_f32_16x16x32_bf16 v[36:39], v[126:129], v[118:121], v[36:39]
	v_mfma_f32_16x16x32_bf16 v[44:47], v[130:133], v[118:121], v[44:47]
	v_mfma_f32_16x16x32_bf16 v[24:27], v[134:137], v[118:121], v[24:27]
	ds_read_b128 v[118:121], v18 offset:3072
	s_waitcnt lgkmcnt(0)
	v_mfma_f32_16x16x32_bf16 v[56:59], v[122:125], v[118:121], v[56:59]
	v_mfma_f32_16x16x32_bf16 v[60:63], v[126:129], v[118:121], v[60:63]
	v_mfma_f32_16x16x32_bf16 v[94:97], v[130:133], v[118:121], v[94:97]
	v_mfma_f32_16x16x32_bf16 v[52:55], v[134:137], v[118:121], v[52:55]
	ds_read_b128 v[118:121], v18 offset:5120
	s_waitcnt lgkmcnt(0)
	v_mfma_f32_16x16x32_bf16 v[106:109], v[122:125], v[118:121], v[106:109]
	v_mfma_f32_16x16x32_bf16 v[110:113], v[126:129], v[118:121], v[110:113]
	v_mfma_f32_16x16x32_bf16 v[114:117], v[130:133], v[118:121], v[114:117]
	v_mfma_f32_16x16x32_bf16 v[98:101], v[134:137], v[118:121], v[98:101]
	ds_read_b128 v[118:121], v18 offset:7168
	s_waitcnt vmcnt(0)
	s_waitcnt lgkmcnt(0)
	s_barrier
	global_load_lds_dwordx4 v[64:65], off
	v_lshl_add_u64 v[64:65], v[4:5], 0, s[22:23]
	s_mov_b32 m0, s57
	s_waitcnt lgkmcnt(0)
	v_mfma_f32_16x16x32_bf16 v[20:23], v[122:125], v[118:121], v[20:23]
	global_load_lds_dwordx4 v[64:65], off
	v_lshl_add_u64 v[64:65], v[6:7], 0, s[22:23]
	s_mov_b32 m0, s58
	v_mfma_f32_16x16x32_bf16 v[32:35], v[126:129], v[118:121], v[32:35]
	global_load_lds_dwordx4 v[64:65], off
	v_lshl_add_u64 v[64:65], v[8:9], 0, s[22:23]
	s_mov_b32 m0, s59
	v_mfma_f32_16x16x32_bf16 v[40:43], v[130:133], v[118:121], v[40:43]
	global_load_lds_dwordx4 v[64:65], off
	v_lshl_add_u64 v[64:65], v[10:11], 0, s[22:23]
	s_mov_b32 m0, s60
	v_mfma_f32_16x16x32_bf16 v[48:51], v[134:137], v[118:121], v[48:51]
	global_load_lds_dwordx4 v[64:65], off
	v_lshl_add_u64 v[64:65], v[12:13], 0, s[22:23]
	s_mov_b32 m0, s61
	s_nop 0
	global_load_lds_dwordx4 v[64:65], off
	v_lshl_add_u64 v[64:65], v[14:15], 0, s[22:23]
	s_mov_b32 m0, s97
	s_nop 0
	global_load_lds_dwordx4 v[64:65], off
	v_lshl_add_u64 v[64:65], v[16:17], 0, s[22:23]
	s_mov_b32 m0, s44
	s_mov_b32 s44, 7
	global_load_lds_dwordx4 v[64:65], off
	ds_read_b128 v[122:125], v19 offset:49152
	ds_read_b128 v[118:121], v18 offset:32768
	ds_read_b128 v[126:129], v19 offset:51200
	ds_read_b128 v[130:133], v19 offset:53248
	ds_read_b128 v[134:137], v19 offset:55296
	s_waitcnt lgkmcnt(0)
	v_mfma_f32_16x16x32_bf16 v[28:31], v[122:125], v[118:121], v[28:31]
	s_mov_b32 m0, s42
	v_mfma_f32_16x16x32_bf16 v[36:39], v[126:129], v[118:121], v[36:39]
	v_mfma_f32_16x16x32_bf16 v[44:47], v[130:133], v[118:121], v[44:47]
	v_mfma_f32_16x16x32_bf16 v[24:27], v[134:137], v[118:121], v[24:27]
	ds_read_b128 v[118:121], v18 offset:34816
	s_waitcnt lgkmcnt(0)
	v_mfma_f32_16x16x32_bf16 v[56:59], v[122:125], v[118:121], v[56:59]
	v_mfma_f32_16x16x32_bf16 v[60:63], v[126:129], v[118:121], v[60:63]
	v_mfma_f32_16x16x32_bf16 v[94:97], v[130:133], v[118:121], v[94:97]
	v_mfma_f32_16x16x32_bf16 v[52:55], v[134:137], v[118:121], v[52:55]
	ds_read_b128 v[118:121], v18 offset:36864
	s_waitcnt lgkmcnt(0)
	v_mfma_f32_16x16x32_bf16 v[106:109], v[122:125], v[118:121], v[106:109]
	v_mfma_f32_16x16x32_bf16 v[110:113], v[126:129], v[118:121], v[110:113]
	v_mfma_f32_16x16x32_bf16 v[114:117], v[130:133], v[118:121], v[114:117]
	v_mfma_f32_16x16x32_bf16 v[98:101], v[134:137], v[118:121], v[98:101]
	ds_read_b128 v[118:121], v18 offset:38912
	s_waitcnt lgkmcnt(0)
	v_mfma_f32_16x16x32_bf16 v[20:23], v[122:125], v[118:121], v[20:23]
	ds_read_b128 v[122:125], v19 offset:50176
	v_mfma_f32_16x16x32_bf16 v[32:35], v[126:129], v[118:121], v[32:35]
	ds_read_b128 v[126:129], v19 offset:52224
	v_mfma_f32_16x16x32_bf16 v[40:43], v[130:133], v[118:121], v[40:43]
	ds_read_b128 v[130:133], v19 offset:54272
	v_mfma_f32_16x16x32_bf16 v[48:51], v[134:137], v[118:121], v[48:51]
	ds_read_b128 v[134:137], v19 offset:56320
	ds_read_b128 v[118:121], v18 offset:33792
	s_waitcnt lgkmcnt(0)
	v_mfma_f32_16x16x32_bf16 v[28:31], v[122:125], v[118:121], v[28:31]
	v_mfma_f32_16x16x32_bf16 v[36:39], v[126:129], v[118:121], v[36:39]
	v_mfma_f32_16x16x32_bf16 v[44:47], v[130:133], v[118:121], v[44:47]
	v_mfma_f32_16x16x32_bf16 v[24:27], v[134:137], v[118:121], v[24:27]
	ds_read_b128 v[118:121], v18 offset:35840
	s_waitcnt lgkmcnt(0)
	v_mfma_f32_16x16x32_bf16 v[56:59], v[122:125], v[118:121], v[56:59]
	v_mfma_f32_16x16x32_bf16 v[60:63], v[126:129], v[118:121], v[60:63]
	v_mfma_f32_16x16x32_bf16 v[94:97], v[130:133], v[118:121], v[94:97]
	v_mfma_f32_16x16x32_bf16 v[52:55], v[134:137], v[118:121], v[52:55]
	ds_read_b128 v[118:121], v18 offset:37888
	s_waitcnt lgkmcnt(0)
	v_mfma_f32_16x16x32_bf16 v[106:109], v[122:125], v[118:121], v[106:109]
	v_mfma_f32_16x16x32_bf16 v[110:113], v[126:129], v[118:121], v[110:113]
	v_mfma_f32_16x16x32_bf16 v[114:117], v[130:133], v[118:121], v[114:117]
	v_mfma_f32_16x16x32_bf16 v[98:101], v[134:137], v[118:121], v[98:101]
	ds_read_b128 v[118:121], v18 offset:39936
	s_waitcnt vmcnt(0)
	s_waitcnt lgkmcnt(0)
	s_barrier
	global_load_lds_dwordx4 v[2:3], off
	v_lshl_add_u64 v[2:3], v[4:5], 0, s[26:27]
	s_mov_b32 m0, s43
	s_waitcnt lgkmcnt(0)
	v_mfma_f32_16x16x32_bf16 v[20:23], v[122:125], v[118:121], v[20:23]
	global_load_lds_dwordx4 v[2:3], off
	v_lshl_add_u64 v[2:3], v[6:7], 0, s[26:27]
	s_mov_b32 m0, s50
	v_mfma_f32_16x16x32_bf16 v[32:35], v[126:129], v[118:121], v[32:35]
	global_load_lds_dwordx4 v[2:3], off
	v_lshl_add_u64 v[2:3], v[8:9], 0, s[26:27]
	s_mov_b32 m0, s51
	v_mfma_f32_16x16x32_bf16 v[6:9], v[134:137], v[118:121], v[48:51]
	global_load_lds_dwordx4 v[2:3], off
	v_lshl_add_u64 v[2:3], v[10:11], 0, s[26:27]
	s_mov_b32 m0, s52
	v_mfma_f32_16x16x32_bf16 v[40:43], v[130:133], v[118:121], v[40:43]
	global_load_lds_dwordx4 v[2:3], off
	v_lshl_add_u64 v[2:3], v[12:13], 0, s[26:27]
	s_mov_b32 m0, s53
	s_mov_b32 s50, 0x40000
	global_load_lds_dwordx4 v[2:3], off
	v_lshl_add_u64 v[2:3], v[14:15], 0, s[26:27]
	s_mov_b32 m0, s54
	s_mov_b64 s[42:43], 0
	global_load_lds_dwordx4 v[2:3], off
	v_lshl_add_u64 v[2:3], v[16:17], 0, s[26:27]
	s_mov_b32 m0, s55
	s_movk_i32 s51, 0x200
	global_load_lds_dwordx4 v[2:3], off
	ds_read_b128 v[2:5], v19 offset:16384
	ds_read_b128 v[10:13], v18
	s_waitcnt lgkmcnt(0)
	v_mfma_f32_16x16x32_bf16 v[14:17], v[2:5], v[10:13], v[28:31]
	s_nop 2
	ds_read_b128 v[28:31], v19 offset:18432
	ds_read_b128 v[48:51], v19 offset:20480
	ds_read_b128 v[156:159], v19 offset:19456
	s_waitcnt lgkmcnt(0)
	v_mfma_f32_16x16x32_bf16 v[118:121], v[48:51], v[10:13], v[44:47]
	s_nop 2
	ds_read_b128 v[44:47], v19 offset:22528
	ds_read_b128 v[160:163], v19 offset:21504
	ds_read_b128 v[138:141], v19 offset:17408
	v_mfma_f32_16x16x32_bf16 v[36:39], v[28:31], v[10:13], v[36:39]
	s_waitcnt lgkmcnt(0)
	v_mfma_f32_16x16x32_bf16 v[10:13], v[44:47], v[10:13], v[24:27]
	s_nop 2
	ds_read_b128 v[24:27], v18 offset:2048
	s_waitcnt lgkmcnt(0)
	v_mfma_f32_16x16x32_bf16 v[122:125], v[2:5], v[24:27], v[56:59]
	v_mfma_f32_16x16x32_bf16 v[126:129], v[28:31], v[24:27], v[60:63]
	v_mfma_f32_16x16x32_bf16 v[94:97], v[48:51], v[24:27], v[94:97]
	v_mfma_f32_16x16x32_bf16 v[24:27], v[44:47], v[24:27], v[52:55]
	s_nop 2
	ds_read_b128 v[52:55], v18 offset:4096
	s_waitcnt lgkmcnt(0)
	v_mfma_f32_16x16x32_bf16 v[106:109], v[2:5], v[52:55], v[106:109]
	v_mfma_f32_16x16x32_bf16 v[110:113], v[28:31], v[52:55], v[110:113]
	v_mfma_f32_16x16x32_bf16 v[114:117], v[48:51], v[52:55], v[114:117]
	v_mfma_f32_16x16x32_bf16 v[98:101], v[44:47], v[52:55], v[98:101]
	ds_read_b128 v[52:55], v18 offset:6144
	s_waitcnt lgkmcnt(0)
	v_mfma_f32_16x16x32_bf16 v[152:155], v[44:47], v[52:55], v[6:9]
	s_nop 2
	ds_read_b128 v[6:9], v18 offset:1024
	s_waitcnt lgkmcnt(0)
	v_mfma_f32_16x16x32_bf16 v[58:61], v[160:163], v[6:9], v[118:121]
	s_nop 2
	ds_read_b128 v[118:121], v19 offset:23552
	v_mfma_f32_16x16x32_bf16 v[2:5], v[2:5], v[52:55], v[20:23]
	v_mfma_f32_16x16x32_bf16 v[130:133], v[28:31], v[52:55], v[32:35]
	v_mfma_f32_16x16x32_bf16 v[134:137], v[48:51], v[52:55], v[40:43]
	v_mfma_f32_16x16x32_bf16 v[46:49], v[138:141], v[6:9], v[14:17]
	v_mfma_f32_16x16x32_bf16 v[50:53], v[156:159], v[6:9], v[36:39]
	s_waitcnt lgkmcnt(0)
	v_mfma_f32_16x16x32_bf16 v[62:65], v[118:121], v[6:9], v[10:13]
	ds_read_b128 v[6:9], v18 offset:3072
	s_waitcnt lgkmcnt(0)
	v_mfma_f32_16x16x32_bf16 v[54:57], v[138:141], v[6:9], v[122:125]
	v_mfma_f32_16x16x32_bf16 v[34:37], v[156:159], v[6:9], v[126:129]
	v_mfma_f32_16x16x32_bf16 v[30:33], v[160:163], v[6:9], v[94:97]
	v_mfma_f32_16x16x32_bf16 v[22:25], v[118:121], v[6:9], v[24:27]
	ds_read_b128 v[6:9], v18 offset:5120
	s_nop 0
	v_lshl_add_u64 v[94:95], v[86:87], 0, s[2:3]
	v_lshl_add_u64 v[96:97], v[88:89], 0, s[2:3]
	s_waitcnt lgkmcnt(0)
	v_mfma_f32_16x16x32_bf16 v[38:41], v[138:141], v[6:9], v[106:109]
	s_nop 2
	ds_read_b128 v[106:109], v18 offset:7168
	v_mfma_f32_16x16x32_bf16 v[14:17], v[156:159], v[6:9], v[110:113]
	v_mfma_f32_16x16x32_bf16 v[10:13], v[160:163], v[6:9], v[114:117]
	v_mfma_f32_16x16x32_bf16 v[6:9], v[118:121], v[6:9], v[98:101]
	s_waitcnt lgkmcnt(0)
	v_mfma_f32_16x16x32_bf16 v[42:45], v[138:141], v[106:109], v[2:5]
	s_nop 0
	v_lshl_add_u64 v[98:99], v[90:91], 0, s[2:3]
	v_lshl_add_u64 v[100:101], v[92:93], 0, s[2:3]
	v_mfma_f32_16x16x32_bf16 v[18:21], v[156:159], v[106:109], v[130:133]
	v_mfma_f32_16x16x32_bf16 v[26:29], v[160:163], v[106:109], v[134:137]
	v_mfma_f32_16x16x32_bf16 v[2:5], v[118:121], v[106:109], v[152:155]
	s_branch .LBB0_63
	.p2align 8

.LBB0_275:
	s_or_b64 exec, exec, s[12:13]
	s_waitcnt lgkmcnt(0)
	v_sub_f32_e32 v4, v15, v4
	v_mul_f32_e32 v4, 0x3fb8aa3b, v4
	v_exp_f32_e32 v4, v4
	v_cmp_gt_i32_e64 s[40:41], v10, v48
	v_mul_f32_e32 v11, v6, v11
	v_mul_f32_e32 v17, v7, v23
	v_mul_f32_e32 v22, v8, v22
	v_mul_f32_e32 v15, v7, v20
	v_mul_f32_e32 v20, v6, v21
	v_cndmask_b32_e64 v4, v4, 0, s[40:41]
	v_mul_f32_e32 v6, v9, v3
	v_mul_f32_e32 v8, v8, v24
	v_cvt_pk_bf16_f32 v7, v22, v6
	v_cvt_pk_bf16_f32 v6, v11, v17
	v_mul_f32_e32 v11, v9, v4
	v_cvt_pk_bf16_f32 v8, v11, v8
	v_mul_f32_e32 v11, v5, v13
	v_mul_f32_e32 v3, v11, v3
	v_cndmask_b32_e64 v3, 0, v3, s[40:41]
	ds_write_b32 v2, v3 offset:12
	v_mul_f32_e32 v2, v5, v12
	v_mul_f32_e32 v2, v2, v4
	v_sub_u32_e32 v3, v16, v48
	v_cndmask_b32_e64 v2, 0, v2, s[0:1]
	v_lshl_add_u32 v3, v3, 2, 0
	ds_write_b32 v3, v2 offset:16892
	v_lshlrev_b32_e32 v2, 7, v10
	v_mov_b32_e32 v3, v0
	v_lshl_add_u64 v[4:5], v[30:31], 0, v[2:3]
	v_xor_b32_e32 v2, 0x1f80, v2
	v_cvt_pk_bf16_f32 v9, v15, v20
	v_lshl_add_u64 v[2:3], v[46:47], 0, v[2:3]
	global_store_dwordx2 v[4:5], v[6:7], off
	global_store_dwordx2 v[2:3], v[8:9], off
	s_waitcnt lgkmcnt(0)
	s_barrier
	s_and_saveexec_b64 s[0:1], vcc
	s_cbranch_execz .LBB0_277
	s_movk_i32 s2, 0x4100
	v_mul_lo_u32 v3, v68, s2
	v_add_u32_e32 v4, 0, v3
	v_and_b32_e32 v3, 48, v1
	v_mul_u32_u24_e32 v5, 0x104, v3
	v_lshlrev_b32_e32 v6, 2, v3
	v_add3_u32 v5, v4, v5, v6
	ds_read_b32 v16, v5 offset:260
	ds_read_b64 v[20:21], v5 offset:520
	ds_read_b32 v17, v5 offset:780
	ds_read_b64 v[22:23], v5 offset:784
	ds_read_b128 v[46:49], v5 offset:1040
	ds_read_b32 v24, v5 offset:1300
	ds_read_b64 v[30:31], v5 offset:1304
	ds_read_b64 v[50:51], v5 offset:1312
	ds_read_b64 v[52:53], v5 offset:1560
	ds_read_b128 v[54:57], v5 offset:1568
	ds_read_b32 v25, v5 offset:1820
	ds_read_b128 v[58:61], v5 offset:1824
	ds_read_b64 v[62:63], v5 offset:1840
	ds_read_b128 v[64:67], v5 offset:2080
	ds_read_b128 v[70:73], v5 offset:2096
	ds_read_b32 v74, v5 offset:2340
	ds_read_b64 v[76:77], v5 offset:2344
	ds_read_b128 v[78:81], v5 offset:2352
	ds_read_b64 v[82:83], v5 offset:2368
	ds_read_b64 v[84:85], v5 offset:2600
	ds_read_b128 v[90:93], v5 offset:2608
	ds_read_b128 v[152:155], v5 offset:2624
	ds_read_b32 v75, v5 offset:2860
	ds_read_b128 v[156:159], v5 offset:2864
	ds_read_b128 v[160:163], v5 offset:2880
	ds_read_b64 v[86:87], v5 offset:2896
	ds_read_b128 v[164:167], v5 offset:3120
	ds_read_b128 v[168:171], v5 offset:3136
	ds_read_b128 v[234:237], v5 offset:3152
	ds_read_b32 v88, v5 offset:3380
	ds_read_b64 v[94:95], v5 offset:3384
	ds_read_b128 v[238:241], v5 offset:3392
	ds_read_b128 v[250:253], v5 offset:3408
	ds_read_b64 v[242:243], v5 offset:3424
	v_cmp_eq_u32_e32 vcc, 0, v37
	v_cndmask_b32_e64 v27, 0, 1.0, vcc
	v_cmp_eq_u32_e32 vcc, 1, v37
	s_waitcnt lgkmcnt(15)
	v_cndmask_b32_e64 v33, 0, 1.0, vcc
	v_fma_f32 v33, -v27, v16, v33
	v_cmp_eq_u32_e32 vcc, 2, v37
	s_waitcnt lgkmcnt(15)
	v_cndmask_b32_e64 v39, 0, 1.0, vcc
	v_fma_f32 v39, -v27, v20, v39
	v_fma_f32 v39, -v33, v21, v39
	v_cmp_eq_u32_e32 vcc, 3, v37
	s_waitcnt lgkmcnt(15)
	v_cndmask_b32_e64 v11, 0, 1.0, vcc
	v_fma_f32 v11, -v27, v17, v11
	v_fma_f32 v11, -v33, v22, v11
	v_fma_f32 v11, -v39, v23, v11
	v_cmp_eq_u32_e32 vcc, 4, v37
	s_waitcnt lgkmcnt(15)
	v_cndmask_b32_e64 v15, 0, 1.0, vcc
	v_fma_f32 v15, -v27, v46, v15
	v_fma_f32 v15, -v33, v47, v15
	v_fma_f32 v15, -v39, v48, v15
	v_fma_f32 v15, -v11, v49, v15
	v_cmp_eq_u32_e32 vcc, 5, v37
	s_waitcnt lgkmcnt(15)
	v_cndmask_b32_e64 v29, 0, 1.0, vcc
	v_fma_f32 v29, -v27, v24, v29
	v_fma_f32 v29, -v33, v30, v29
	v_fma_f32 v29, -v39, v31, v29
	v_fma_f32 v29, -v11, v50, v29
	v_fma_f32 v29, -v15, v51, v29
	v_cmp_eq_u32_e32 vcc, 6, v37
	s_waitcnt lgkmcnt(15)
	v_cndmask_b32_e64 v69, 0, 1.0, vcc
	v_fma_f32 v69, -v27, v52, v69
	v_fma_f32 v69, -v33, v53, v69
	v_fma_f32 v69, -v39, v54, v69
	v_fma_f32 v69, -v11, v55, v69
	v_fma_f32 v69, -v15, v56, v69
	v_fma_f32 v69, -v29, v57, v69
	v_cmp_eq_u32_e32 vcc, 7, v37
	s_waitcnt lgkmcnt(15)
	v_cndmask_b32_e64 v151, 0, 1.0, vcc
	v_fma_f32 v151, -v27, v25, v151
	v_fma_f32 v151, -v33, v58, v151
	v_fma_f32 v151, -v39, v59, v151
	v_fma_f32 v151, -v11, v60, v151
	v_fma_f32 v151, -v15, v61, v151
	v_fma_f32 v151, -v29, v62, v151
	v_fma_f32 v151, -v69, v63, v151
	v_cmp_eq_u32_e32 vcc, 8, v37
	s_waitcnt lgkmcnt(15)
	v_cndmask_b32_e64 v233, 0, 1.0, vcc
	v_fma_f32 v233, -v27, v64, v233
	v_fma_f32 v233, -v33, v65, v233
	v_fma_f32 v233, -v39, v66, v233
	v_fma_f32 v233, -v11, v67, v233
	v_fma_f32 v233, -v15, v70, v233
	v_fma_f32 v233, -v29, v71, v233
	v_fma_f32 v233, -v69, v72, v233
	v_fma_f32 v233, -v151, v73, v233
	v_cmp_eq_u32_e32 vcc, 9, v37
	s_waitcnt lgkmcnt(15)
	v_cndmask_b32_e64 v249, 0, 1.0, vcc
	v_fma_f32 v249, -v27, v74, v249
	v_fma_f32 v249, -v33, v76, v249
	v_fma_f32 v249, -v39, v77, v249
	v_fma_f32 v249, -v11, v78, v249
	v_fma_f32 v249, -v15, v79, v249
	v_fma_f32 v249, -v29, v80, v249
	v_fma_f32 v249, -v69, v81, v249
	v_fma_f32 v249, -v151, v82, v249
	v_fma_f32 v249, -v233, v83, v249
	ds_read_b64 v[16:17], v5 offset:3640
	ds_read_b128 v[20:23], v5 offset:3648
	ds_read_b128 v[46:49], v5 offset:3664
	ds_read_b128 v[50:53], v5 offset:3680
	ds_read_b32 v244, v5 offset:3900
	ds_read_b128 v[54:57], v5 offset:3904
	ds_read_b128 v[58:61], v5 offset:3920
	ds_read_b128 v[62:65], v5 offset:3936
	ds_read_b64 v[24:25], v5 offset:3952
	v_cmp_eq_u32_e32 vcc, 10, v37
	s_waitcnt lgkmcnt(15)
	v_cndmask_b32_e64 v6, 0, 1.0, vcc
	v_fma_f32 v6, -v27, v84, v6
	v_fma_f32 v6, -v33, v85, v6
	v_fma_f32 v6, -v39, v90, v6
	v_fma_f32 v6, -v11, v91, v6
	v_fma_f32 v6, -v15, v92, v6
	v_fma_f32 v6, -v29, v93, v6
	v_fma_f32 v6, -v69, v152, v6
	v_fma_f32 v6, -v151, v153, v6
	v_fma_f32 v6, -v233, v154, v6
	v_fma_f32 v6, -v249, v155, v6
	v_cmp_eq_u32_e32 vcc, 11, v37
	s_waitcnt lgkmcnt(15)
	v_cndmask_b32_e64 v7, 0, 1.0, vcc
	v_fma_f32 v7, -v27, v75, v7
	v_fma_f32 v7, -v33, v156, v7
	v_fma_f32 v7, -v39, v157, v7
	v_fma_f32 v7, -v11, v158, v7
	v_fma_f32 v7, -v15, v159, v7
	v_fma_f32 v7, -v29, v160, v7
	v_fma_f32 v7, -v69, v161, v7
	v_fma_f32 v7, -v151, v162, v7
	v_fma_f32 v7, -v233, v163, v7
	v_fma_f32 v7, -v249, v86, v7
	v_fma_f32 v7, -v6, v87, v7
	v_cmp_eq_u32_e32 vcc, 12, v37
	s_waitcnt lgkmcnt(14)
	v_cndmask_b32_e64 v8, 0, 1.0, vcc
	v_fma_f32 v8, -v27, v164, v8
	v_fma_f32 v8, -v33, v165, v8
	v_fma_f32 v8, -v39, v166, v8
	v_fma_f32 v8, -v11, v167, v8
	v_fma_f32 v8, -v15, v168, v8
	v_fma_f32 v8, -v29, v169, v8
	v_fma_f32 v8, -v69, v170, v8
	v_fma_f32 v8, -v151, v171, v8
	v_fma_f32 v8, -v233, v234, v8
	v_fma_f32 v8, -v249, v235, v8
	v_fma_f32 v8, -v6, v236, v8
	v_fma_f32 v8, -v7, v237, v8
	v_cmp_eq_u32_e32 vcc, 13, v37
	s_waitcnt lgkmcnt(9)
	v_cndmask_b32_e64 v9, 0, 1.0, vcc
	v_fma_f32 v9, -v27, v88, v9
	v_fma_f32 v9, -v33, v94, v9
	v_fma_f32 v9, -v39, v95, v9
	v_fma_f32 v9, -v11, v238, v9
	v_fma_f32 v9, -v15, v239, v9
	v_fma_f32 v9, -v29, v240, v9
	v_fma_f32 v9, -v69, v241, v9
	v_fma_f32 v9, -v151, v250, v9
	v_fma_f32 v9, -v233, v251, v9
	v_fma_f32 v9, -v249, v252, v9
	v_fma_f32 v9, -v6, v253, v9
	v_fma_f32 v9, -v7, v242, v9
	v_fma_f32 v9, -v8, v243, v9
	v_cmp_eq_u32_e32 vcc, 14, v37
	s_waitcnt lgkmcnt(5)
	v_cndmask_b32_e64 v12, 0, 1.0, vcc
	v_fma_f32 v12, -v27, v16, v12
	v_fma_f32 v12, -v33, v17, v12
	v_fma_f32 v12, -v39, v20, v12
	v_fma_f32 v12, -v11, v21, v12
	v_fma_f32 v12, -v15, v22, v12
	v_fma_f32 v12, -v29, v23, v12
	v_fma_f32 v12, -v69, v46, v12
	v_fma_f32 v12, -v151, v47, v12
	v_fma_f32 v12, -v233, v48, v12
	v_fma_f32 v12, -v249, v49, v12
	v_fma_f32 v12, -v6, v50, v12
	v_fma_f32 v12, -v7, v51, v12
	v_fma_f32 v12, -v8, v52, v12
	v_fma_f32 v12, -v9, v53, v12
	v_cmp_eq_u32_e32 vcc, 15, v37
	s_waitcnt lgkmcnt(0)
	v_cndmask_b32_e64 v13, 0, 1.0, vcc
	v_fma_f32 v13, -v27, v244, v13
	v_fma_f32 v13, -v33, v54, v13
	v_fma_f32 v13, -v39, v55, v13
	v_fma_f32 v13, -v11, v56, v13
	v_fma_f32 v13, -v15, v57, v13
	v_fma_f32 v13, -v29, v58, v13
	v_fma_f32 v13, -v69, v59, v13
	v_fma_f32 v13, -v151, v60, v13
	v_fma_f32 v13, -v233, v61, v13
	v_fma_f32 v13, -v249, v62, v13
	v_fma_f32 v13, -v6, v63, v13
	v_fma_f32 v13, -v7, v64, v13
	v_fma_f32 v13, -v8, v65, v13
	v_fma_f32 v13, -v9, v24, v13
	v_fma_f32 v13, -v12, v25, v13
	v_add_u32_e32 v5, v5, v41
	ds_write_b32 v5, v27
	ds_write_b32 v5, v33 offset:260
	ds_write_b32 v5, v39 offset:520
	ds_write_b32 v5, v11 offset:780
	ds_write_b32 v5, v15 offset:1040
	ds_write_b32 v5, v29 offset:1300
	ds_write_b32 v5, v69 offset:1560
	ds_write_b32 v5, v151 offset:1820
	ds_write_b32 v5, v233 offset:2080
	ds_write_b32 v5, v249 offset:2340
	ds_write_b32 v5, v6 offset:2600
	ds_write_b32 v5, v7 offset:2860
	ds_write_b32 v5, v8 offset:3120
	ds_write_b32 v5, v9 offset:3380
	ds_write_b32 v5, v12 offset:3640
	ds_write_b32 v5, v13 offset:3900
	v_mul_u32_u24_e32 v2, 0x104, v37
	s_movk_i32 s2, 0x1040
	v_add3_u32 v2, v2, v4, s2
	s_movk_i32 s2, 0x104
	v_add_u32_e32 v5, v4, v41
	v_lshl_add_u32 v4, v45, 2, v2
	v_add_u32_e32 v11, v2, v3
	v_mad_u32_u24 v2, v45, s2, v5
	ds_read_b32 v15, v2
	ds_read2_b32 v[12:13], v4 offset1:4
	ds_read2_b32 v[16:17], v4 offset0:8 offset1:12
	s_waitcnt lgkmcnt(1)
	v_mfma_f32_16x16x4_f32 v[6:9], v12, v15, 0
	ds_read_b32 v24, v2 offset:1040
	ds_read_b32 v25, v2 offset:2080
	ds_read_b32 v27, v2 offset:3120
	s_movk_i32 s2, 0x410
	v_mad_u32_u24 v3, v45, s2, v5
	v_add_u32_e32 v48, 0x2140, v11
	s_waitcnt lgkmcnt(2)
	v_mfma_f32_16x16x4_f32 v[6:9], v13, v24, v[6:9]
	ds_read2_b32 v[12:13], v11 offset0:16 offset1:17
	s_waitcnt lgkmcnt(2)
	v_mfma_f32_16x16x4_f32 v[6:9], v16, v25, v[6:9]
	s_waitcnt lgkmcnt(1)
	v_mfma_f32_16x16x4_f32 v[6:9], v17, v27, v[6:9]
	s_waitcnt lgkmcnt(0)
	s_nop 8
	v_mfma_f32_16x16x4_f32 v[20:23], v12, v6, 0
	v_mfma_f32_16x16x4_f32 v[20:23], v13, v7, v[20:23]
	ds_read2_b32 v[6:7], v11 offset0:18 offset1:19
	s_waitcnt lgkmcnt(0)
	v_mfma_f32_16x16x4_f32 v[20:23], v6, v8, v[20:23]
	v_mfma_f32_16x16x4_f32 v[6:9], v7, v9, v[20:23]
	s_nop 9
	v_xor_b32_e32 v6, 0x80000000, v6
	v_xor_b32_e32 v5, 0x80000000, v7
	v_add_u32_e32 v7, 0x1000, v3
	ds_write2_b32 v7, v6, v5 offset0:16 offset1:81
	v_xor_b32_e32 v5, 0x80000000, v8
	v_xor_b32_e32 v6, 0x80000000, v9
	ds_write2_b32 v7, v5, v6 offset0:146 offset1:211
	v_add_u32_e32 v6, 0x1000, v4
	ds_read2_b32 v[12:13], v6 offset0:16 offset1:20
	ds_read2_b32 v[16:17], v6 offset0:24 offset1:28
	s_waitcnt lgkmcnt(1)
	v_mfma_f32_16x16x4_f32 v[6:9], v12, v15, 0
	ds_read_b32 v12, v4 offset:4224
	ds_read_b32 v29, v2 offset:4160
	v_add_u32_e32 v5, 0x10c0, v11
	v_mfma_f32_16x16x4_f32 v[6:9], v13, v24, v[6:9]
	s_waitcnt lgkmcnt(2)
	v_mfma_f32_16x16x4_f32 v[6:9], v16, v25, v[6:9]
	v_add_u32_e32 v16, 0x10c8, v11
	v_add_u32_e32 v11, 0x2148, v11
	v_mfma_f32_16x16x4_f32 v[6:9], v17, v27, v[6:9]
	s_waitcnt lgkmcnt(0)
	v_mfma_f32_16x16x4_f32 v[6:9], v12, v29, v[6:9]
	ds_read_b32 v12, v4 offset:4240
	ds_read_b32 v30, v2 offset:5200
	s_waitcnt lgkmcnt(0)
	v_mfma_f32_16x16x4_f32 v[6:9], v12, v30, v[6:9]
	ds_read_b32 v12, v4 offset:4256
	ds_read_b32 v31, v2 offset:6240
	s_waitcnt lgkmcnt(0)
	v_mfma_f32_16x16x4_f32 v[6:9], v12, v31, v[6:9]
	ds_read_b32 v12, v4 offset:4272
	ds_read_b32 v33, v2 offset:7280
	s_waitcnt lgkmcnt(0)
	v_mfma_f32_16x16x4_f32 v[6:9], v12, v33, v[6:9]
	ds_read2_b32 v[12:13], v5 offset1:1
	s_waitcnt lgkmcnt(0)
	s_nop 7
	v_mfma_f32_16x16x4_f32 v[20:23], v12, v6, 0
	v_mfma_f32_16x16x4_f32 v[20:23], v13, v7, v[20:23]
	ds_read2_b32 v[6:7], v16 offset1:1
	s_waitcnt lgkmcnt(0)
	v_mfma_f32_16x16x4_f32 v[20:23], v6, v8, v[20:23]
	v_mfma_f32_16x16x4_f32 v[6:9], v7, v9, v[20:23]
	s_nop 9
	v_xor_b32_e32 v6, 0x80000000, v6
	ds_write_b32 v3, v6 offset:8320
	v_xor_b32_e32 v6, 0x80000000, v7
	ds_write_b32 v3, v6 offset:8580
	v_xor_b32_e32 v6, 0x80000000, v8
	ds_write_b32 v3, v6 offset:8840
	v_xor_b32_e32 v6, 0x80000000, v9
	ds_write_b32 v3, v6 offset:9100
	ds_read_b32 v39, v2 offset:4224
	ds_read_b32 v6, v4 offset:4224
	ds_read_b32 v12, v4 offset:4240
	ds_read_b32 v13, v4 offset:4256
	ds_read_b32 v17, v4 offset:4272
	s_waitcnt lgkmcnt(3)
	v_mfma_f32_16x16x4_f32 v[6:9], v6, v39, 0
	ds_read_b32 v41, v2 offset:5264
	ds_read_b32 v46, v2 offset:6304
	ds_read_b32 v47, v2 offset:7344
	s_waitcnt lgkmcnt(2)
	v_mfma_f32_16x16x4_f32 v[6:9], v12, v41, v[6:9]
	s_waitcnt lgkmcnt(1)
	v_mfma_f32_16x16x4_f32 v[6:9], v13, v46, v[6:9]
	ds_read2_b32 v[12:13], v5 offset1:1
	s_waitcnt lgkmcnt(1)
	v_mfma_f32_16x16x4_f32 v[6:9], v17, v47, v[6:9]
	s_waitcnt lgkmcnt(0)
	s_nop 8
	v_mfma_f32_16x16x4_f32 v[20:23], v12, v6, 0
	v_mfma_f32_16x16x4_f32 v[20:23], v13, v7, v[20:23]
	ds_read2_b32 v[6:7], v16 offset1:1
	s_waitcnt lgkmcnt(0)
	v_mfma_f32_16x16x4_f32 v[20:23], v6, v8, v[20:23]
	v_mfma_f32_16x16x4_f32 v[6:9], v7, v9, v[20:23]
	s_nop 9
	v_xor_b32_e32 v5, 0x80000000, v6
	ds_write_b32 v3, v5 offset:8384
	v_xor_b32_e32 v5, 0x80000000, v7
	ds_write_b32 v3, v5 offset:8644
	v_xor_b32_e32 v5, 0x80000000, v8
	ds_write_b32 v3, v5 offset:8904
	v_xor_b32_e32 v5, 0x80000000, v9
	ds_write_b32 v3, v5 offset:9164
	v_add_u32_e32 v5, 0x2000, v4
	ds_read2_b32 v[12:13], v5 offset0:32 offset1:36
	ds_read2_b32 v[16:17], v5 offset0:40 offset1:44
	s_waitcnt lgkmcnt(1)
	v_mfma_f32_16x16x4_f32 v[6:9], v12, v15, 0
	ds_read_b32 v5, v4 offset:8384
	v_mfma_f32_16x16x4_f32 v[6:9], v13, v24, v[6:9]
	s_waitcnt lgkmcnt(1)
	v_mfma_f32_16x16x4_f32 v[6:9], v16, v25, v[6:9]
	v_mfma_f32_16x16x4_f32 v[6:9], v17, v27, v[6:9]
	s_waitcnt lgkmcnt(0)
	v_mfma_f32_16x16x4_f32 v[6:9], v5, v29, v[6:9]
	ds_read_b32 v5, v4 offset:8400
	s_waitcnt lgkmcnt(0)
	v_mfma_f32_16x16x4_f32 v[6:9], v5, v30, v[6:9]
	ds_read_b32 v5, v4 offset:8416
	s_waitcnt lgkmcnt(0)
	v_mfma_f32_16x16x4_f32 v[6:9], v5, v31, v[6:9]
	ds_read_b32 v5, v4 offset:8432
	s_waitcnt lgkmcnt(0)
	v_mfma_f32_16x16x4_f32 v[6:9], v5, v33, v[6:9]
	ds_read_b32 v5, v4 offset:8448
	ds_read_b32 v12, v2 offset:8320
	s_waitcnt lgkmcnt(0)
	v_mfma_f32_16x16x4_f32 v[6:9], v5, v12, v[6:9]
	ds_read_b32 v5, v4 offset:8464
	ds_read_b32 v12, v2 offset:9360
	s_waitcnt lgkmcnt(0)
	v_mfma_f32_16x16x4_f32 v[6:9], v5, v12, v[6:9]
	ds_read_b32 v5, v4 offset:8480
	ds_read_b32 v12, v2 offset:10400
	s_waitcnt lgkmcnt(0)
	v_mfma_f32_16x16x4_f32 v[6:9], v5, v12, v[6:9]
	ds_read_b32 v5, v4 offset:8496
	ds_read_b32 v12, v2 offset:11440
	s_waitcnt lgkmcnt(0)
	v_mfma_f32_16x16x4_f32 v[6:9], v5, v12, v[6:9]
	ds_read2_b32 v[12:13], v48 offset1:1
	s_waitcnt lgkmcnt(0)
	s_nop 7
	v_mfma_f32_16x16x4_f32 v[20:23], v12, v6, 0
	v_mfma_f32_16x16x4_f32 v[20:23], v13, v7, v[20:23]
	ds_read2_b32 v[6:7], v11 offset1:1
	s_waitcnt lgkmcnt(0)
	v_mfma_f32_16x16x4_f32 v[20:23], v6, v8, v[20:23]
	v_mfma_f32_16x16x4_f32 v[6:9], v7, v9, v[20:23]
	s_nop 9
	v_xor_b32_e32 v5, 0x80000000, v6
	ds_write_b32 v3, v5 offset:12480
	v_xor_b32_e32 v5, 0x80000000, v7
	ds_write_b32 v3, v5 offset:12740
	v_xor_b32_e32 v5, 0x80000000, v8
	ds_write_b32 v3, v5 offset:13000
	v_xor_b32_e32 v5, 0x80000000, v9
	ds_write_b32 v3, v5 offset:13260
	ds_read_b32 v5, v4 offset:8384
	ds_read_b32 v12, v4 offset:8400
	ds_read_b32 v13, v4 offset:8416
	ds_read_b32 v15, v4 offset:8432
	s_waitcnt lgkmcnt(3)
	v_mfma_f32_16x16x4_f32 v[6:9], v5, v39, 0
	s_waitcnt lgkmcnt(2)
	v_mfma_f32_16x16x4_f32 v[6:9], v12, v41, v[6:9]
	ds_read_b32 v5, v4 offset:8448
	ds_read_b32 v12, v2 offset:8384
	s_waitcnt lgkmcnt(3)
	v_mfma_f32_16x16x4_f32 v[6:9], v13, v46, v[6:9]
	s_waitcnt lgkmcnt(2)
	v_mfma_f32_16x16x4_f32 v[6:9], v15, v47, v[6:9]
	s_waitcnt lgkmcnt(0)
	v_mfma_f32_16x16x4_f32 v[6:9], v5, v12, v[6:9]
	ds_read_b32 v5, v4 offset:8464
	ds_read_b32 v12, v2 offset:9424
	s_waitcnt lgkmcnt(0)
	v_mfma_f32_16x16x4_f32 v[6:9], v5, v12, v[6:9]
	ds_read_b32 v5, v4 offset:8480
	ds_read_b32 v12, v2 offset:10464
	s_waitcnt lgkmcnt(0)
	v_mfma_f32_16x16x4_f32 v[6:9], v5, v12, v[6:9]
	ds_read_b32 v5, v4 offset:8496
	ds_read_b32 v12, v2 offset:11504
	s_waitcnt lgkmcnt(0)
	v_mfma_f32_16x16x4_f32 v[6:9], v5, v12, v[6:9]
	ds_read2_b32 v[12:13], v48 offset1:1
	s_waitcnt lgkmcnt(0)
	s_nop 7
	v_mfma_f32_16x16x4_f32 v[20:23], v12, v6, 0
	v_mfma_f32_16x16x4_f32 v[20:23], v13, v7, v[20:23]
	ds_read2_b32 v[6:7], v11 offset1:1
	s_waitcnt lgkmcnt(0)
	v_mfma_f32_16x16x4_f32 v[20:23], v6, v8, v[20:23]
	v_mfma_f32_16x16x4_f32 v[6:9], v7, v9, v[20:23]
	s_nop 9
	v_xor_b32_e32 v5, 0x80000000, v6
	ds_write_b32 v3, v5 offset:12544
	v_xor_b32_e32 v5, 0x80000000, v7
	ds_write_b32 v3, v5 offset:12804
	v_xor_b32_e32 v5, 0x80000000, v8
	ds_write_b32 v3, v5 offset:13064
	v_xor_b32_e32 v5, 0x80000000, v9
	ds_write_b32 v3, v5 offset:13324
	ds_read_b32 v5, v2 offset:8448
	ds_read_b32 v6, v4 offset:8448
	ds_read_b32 v8, v4 offset:8464
	ds_read_b32 v9, v4 offset:8480
	ds_read_b32 v12, v4 offset:8496
	s_waitcnt lgkmcnt(3)
	v_mfma_f32_16x16x4_f32 v[4:7], v6, v5, 0
	ds_read_b32 v13, v2 offset:9488
	s_waitcnt lgkmcnt(0)
	v_mfma_f32_16x16x4_f32 v[4:7], v8, v13, v[4:7]
	ds_read_b32 v8, v2 offset:10528
	ds_read_b32 v2, v2 offset:11568
	s_waitcnt lgkmcnt(1)
	v_mfma_f32_16x16x4_f32 v[4:7], v9, v8, v[4:7]
	ds_read2_b32 v[8:9], v48 offset1:1
	s_waitcnt lgkmcnt(1)
	v_mfma_f32_16x16x4_f32 v[4:7], v12, v2, v[4:7]
	s_waitcnt lgkmcnt(0)
	s_nop 8
	v_mfma_f32_16x16x4_f32 v[20:23], v8, v4, 0
	v_mfma_f32_16x16x4_f32 v[20:23], v9, v5, v[20:23]
	ds_read2_b32 v[4:5], v11 offset1:1
	s_waitcnt lgkmcnt(0)
	v_mfma_f32_16x16x4_f32 v[20:23], v4, v6, v[20:23]
	v_mfma_f32_16x16x4_f32 v[4:7], v5, v7, v[20:23]
	s_nop 9
	v_xor_b32_e32 v2, 0x80000000, v4
	ds_write_b32 v3, v2 offset:12608
	v_xor_b32_e32 v2, 0x80000000, v5
	ds_write_b32 v3, v2 offset:12868
	v_xor_b32_e32 v2, 0x80000000, v6
	ds_write_b32 v3, v2 offset:13128
	v_xor_b32_e32 v2, 0x80000000, v7
	ds_write_b32 v3, v2 offset:13388

.LBB0_299:
	s_lshl_b32 s40, s12, 7
	s_ashr_i32 s41, s40, 31
	s_lshl_b32 s0, s56, 7
	s_lshl_b64 s[42:43], s[40:41], 11
	s_add_u32 s44, s24, s42
	s_addc_u32 s45, s25, s43
	s_ashr_i32 s1, s0, 31
	s_lshl_b64 s[48:49], s[0:1], 11
	s_add_u32 s50, s5, s48
	v_readfirstlane_b32 s1, v67
	v_add_u32_e32 v4, 0x4000, v67
	s_waitcnt lgkmcnt(0)
	s_barrier
	s_addc_u32 s51, s96, s49
	v_lshl_add_u64 v[2:3], s[44:45], 0, v[92:93]
	s_mov_b32 m0, s1
	v_readfirstlane_b32 s1, v4
	v_add_u32_e32 v4, 0x1000, v67
	global_load_lds_dwordx4 v[2:3], off
	v_lshl_add_u64 v[2:3], s[50:51], 0, v[92:93]
	s_mov_b32 m0, s1
	v_readfirstlane_b32 s1, v4
	v_add_u32_e32 v4, 0x5000, v67
	global_load_lds_dwordx4 v[2:3], off
	v_lshl_add_u64 v[2:3], s[44:45], 0, v[94:95]
	s_mov_b32 m0, s1
	v_readfirstlane_b32 s1, v4
	v_add_u32_e32 v4, 0x2000, v67
	global_load_lds_dwordx4 v[2:3], off
	v_lshl_add_u64 v[2:3], s[50:51], 0, v[94:95]
	s_mov_b32 m0, s1
	v_readfirstlane_b32 s1, v4
	v_add_u32_e32 v4, 0x6000, v67
	global_load_lds_dwordx4 v[2:3], off
	v_lshl_add_u64 v[2:3], s[44:45], 0, v[96:97]
	s_mov_b32 m0, s1
	v_readfirstlane_b32 s1, v4
	v_add_u32_e32 v4, 0x3000, v67
	global_load_lds_dwordx4 v[2:3], off
	v_lshl_add_u64 v[2:3], s[50:51], 0, v[96:97]
	s_mov_b32 m0, s1
	v_readfirstlane_b32 s1, v4
	v_add_u32_e32 v4, 0x7000, v67
	global_load_lds_dwordx4 v[2:3], off
	v_lshl_add_u64 v[2:3], s[44:45], 0, v[98:99]
	s_mov_b32 m0, s1
	v_readfirstlane_b32 s1, v4
	global_load_lds_dwordx4 v[2:3], off
	v_lshl_add_u64 v[2:3], s[50:51], 0, v[98:99]
	s_mov_b32 m0, s1
	v_lshl_add_u64 v[100:101], v[76:77], 0, s[42:43]
	global_load_lds_dwordx4 v[2:3], off
	v_mov_b32_e32 v2, 0
	v_lshl_add_u64 v[102:103], v[78:79], 0, s[42:43]
	v_lshl_add_u64 v[104:105], v[80:81], 0, s[42:43]
	v_lshl_add_u64 v[106:107], v[82:83], 0, s[42:43]
	v_lshl_add_u64 v[108:109], v[84:85], 0, s[48:49]
	v_lshl_add_u64 v[110:111], v[86:87], 0, s[48:49]
	v_lshl_add_u64 v[112:113], v[88:89], 0, s[48:49]
	v_lshl_add_u64 v[114:115], v[90:91], 0, s[48:49]
	s_mov_b32 s13, 0
	s_mov_b64 s[42:43], 0
	v_mov_b32_e32 v3, v2
	v_mov_b32_e32 v4, v2
	v_mov_b32_e32 v5, v2
	v_mov_b32_e32 v6, v2
	v_mov_b32_e32 v7, v2
	v_mov_b32_e32 v8, v2
	v_mov_b32_e32 v9, v2
	v_mov_b32_e32 v10, v2
	v_mov_b32_e32 v11, v2
	v_mov_b32_e32 v12, v2
	v_mov_b32_e32 v13, v2
	v_mov_b32_e32 v14, v2
	v_mov_b32_e32 v15, v2
	v_mov_b32_e32 v16, v2
	v_mov_b32_e32 v17, v2
	v_mov_b32_e32 v18, v2
	v_mov_b32_e32 v19, v2
	v_mov_b32_e32 v20, v2
	v_mov_b32_e32 v21, v2
	v_mov_b32_e32 v22, v2
	v_mov_b32_e32 v23, v2
	v_mov_b32_e32 v24, v2
	v_mov_b32_e32 v25, v2
	v_mov_b32_e32 v26, v2
	v_mov_b32_e32 v27, v2
	v_mov_b32_e32 v28, v2
	v_mov_b32_e32 v29, v2
	v_mov_b32_e32 v30, v2
	v_mov_b32_e32 v31, v2
	v_mov_b32_e32 v32, v2
	v_mov_b32_e32 v33, v2
	v_mov_b32_e32 v34, v2
	v_mov_b32_e32 v35, v2
	v_mov_b32_e32 v36, v2
	v_mov_b32_e32 v37, v2
	v_mov_b32_e32 v38, v2
	v_mov_b32_e32 v39, v2
	v_mov_b32_e32 v40, v2
	v_mov_b32_e32 v41, v2
	v_mov_b32_e32 v42, v2
	v_mov_b32_e32 v43, v2
	v_mov_b32_e32 v44, v2
	v_mov_b32_e32 v45, v2
	v_mov_b32_e32 v46, v2
	v_mov_b32_e32 v47, v2
	v_mov_b32_e32 v48, v2
	v_mov_b32_e32 v49, v2
	v_mov_b32_e32 v50, v2
	v_mov_b32_e32 v51, v2
	v_mov_b32_e32 v52, v2
	v_mov_b32_e32 v53, v2
	v_mov_b32_e32 v54, v2
	v_mov_b32_e32 v55, v2
	v_mov_b32_e32 v56, v2
	v_mov_b32_e32 v57, v2
	v_mov_b32_e32 v58, v2
	v_mov_b32_e32 v59, v2
	v_mov_b32_e32 v60, v2
	v_mov_b32_e32 v61, v2
	v_mov_b32_e32 v62, v2
	v_mov_b32_e32 v63, v2
	v_mov_b32_e32 v64, v2
	v_mov_b32_e32 v65, v2
	.p2align 8
